# group-barrier arrival is a returning atomic: the last arriver (old count 3) leaves without a poll round trip - on top of v63
# speedup vs baseline: 1.0030x; 1.0030x over previous
.Lmy_gchk_4:
	s_mov_b32 s2, -1
	s_nop 0
	v_mbcnt_lo_u32_b32 v0, s2, 0
	v_mbcnt_hi_u32_b32 v0, s2, v0
	s_nop 0
	v_cmp_eq_u32_e32 vcc, 0, v0
	s_and_saveexec_b64 s[16:17], vcc
	s_cbranch_execz .LBB0_905
	s_cmp_lg_u32 s101, 1
	s_cbranch_scc1 .Lmy_gfull_4
	v_readlane_b32 s2, v253, 37
	v_readlane_b32 s3, v250, 7
	v_readlane_b32 s8, v250, 0
	v_readlane_b32 s9, v250, 1
	s_lshl_b32 s2, s2, 12
	s_add_i32 s2, s2, 0x4000
	s_and_b32 s3, s3, 63
	s_lshl_b32 s3, s3, 6
	s_add_i32 s2, s2, s3
	s_add_u32 s8, s8, 0x70000
	s_addc_u32 s9, s9, 0
	v_mov_b32_e32 v0, s2
	v_mov_b32_e32 v1, 1
	s_waitcnt vmcnt(0) lgkmcnt(0)
	global_atomic_add v2, v0, v1, s[8:9] sc0
	s_mov_b32 s2, 0
	s_waitcnt vmcnt(0)
	v_readfirstlane_b32 s3, v2
	s_cmp_ge_u32 s3, 3
	s_cbranch_scc1 .Lmy_gdone_4

.Lmy_gchk_7:
	s_mov_b32 s0, -1
	s_nop 0
	v_mbcnt_lo_u32_b32 v0, s0, 0
	v_mbcnt_hi_u32_b32 v0, s0, v0
	s_nop 0
	v_cmp_eq_u32_e32 vcc, 0, v0
	s_and_saveexec_b64 s[18:19], vcc
	s_cbranch_execz .LBB0_1297
	s_cmp_lg_u32 s101, 1
	s_cbranch_scc1 .Lmy_gfull_7
	v_readlane_b32 s2, v253, 37
	v_readlane_b32 s3, v250, 7
	v_readlane_b32 s8, v250, 0
	v_readlane_b32 s9, v250, 1
	s_lshl_b32 s2, s2, 12
	s_add_i32 s2, s2, 0x7000
	s_and_b32 s3, s3, 63
	s_lshl_b32 s3, s3, 6
	s_add_i32 s2, s2, s3
	s_add_u32 s8, s8, 0x70000
	s_addc_u32 s9, s9, 0
	v_mov_b32_e32 v0, s2
	v_mov_b32_e32 v1, 1
	s_waitcnt vmcnt(0) lgkmcnt(0)
	global_atomic_add v2, v0, v1, s[8:9] sc0
	s_mov_b32 s2, 0
	s_waitcnt vmcnt(0)
	v_readfirstlane_b32 s3, v2
	s_cmp_ge_u32 s3, 3
	s_cbranch_scc1 .Lmy_gdone_7

.Lmy_gchk_0:
	s_mov_b32 s2, -1
	s_nop 0
	v_mbcnt_lo_u32_b32 v0, s2, 0
	v_mbcnt_hi_u32_b32 v0, s2, v0
	s_nop 0
	v_cmp_eq_u32_e32 vcc, 0, v0
	s_and_saveexec_b64 s[16:17], vcc
	s_cbranch_execz .LBB0_1954
	s_cmp_lg_u32 s101, 1
	s_cbranch_scc1 .Lmy_gfull_0
	v_readlane_b32 s2, v253, 37
	v_readlane_b32 s3, v250, 7
	v_readlane_b32 s8, v250, 0
	v_readlane_b32 s9, v250, 1
	s_lshl_b32 s2, s2, 12
	s_add_i32 s2, s2, 0x0
	s_and_b32 s3, s3, 63
	s_lshl_b32 s3, s3, 6
	s_add_i32 s2, s2, s3
	s_add_u32 s8, s8, 0x70000
	s_addc_u32 s9, s9, 0
	v_mov_b32_e32 v0, s2
	v_mov_b32_e32 v1, 1
	s_waitcnt vmcnt(0) lgkmcnt(0)
	global_atomic_add v2, v0, v1, s[8:9] sc0
	s_mov_b32 s2, 0
	s_waitcnt vmcnt(0)
	v_readfirstlane_b32 s3, v2
	s_cmp_ge_u32 s3, 3
	s_cbranch_scc1 .Lmy_gdone_0

.Lmy_gchk_3:
	s_mov_b32 s2, -1
	s_nop 0
	v_mbcnt_lo_u32_b32 v0, s2, 0
	v_mbcnt_hi_u32_b32 v0, s2, v0
	s_nop 0
	v_cmp_eq_u32_e32 vcc, 0, v0
	s_and_saveexec_b64 s[16:17], vcc
	s_cbranch_execz .LBB0_2032
	s_cmp_lg_u32 s101, 1
	s_cbranch_scc1 .Lmy_gfull_3
	v_readlane_b32 s100, v253, 37
	v_readlane_b32 s3, v250, 7
	v_readlane_b32 s8, v250, 0
	v_readlane_b32 s9, v250, 1
	s_lshl_b32 s12, s100, 12
	s_add_i32 s2, s12, 0x3000
	s_and_b32 s13, s3, 63
	s_lshl_b32 s13, s13, 6
	s_add_i32 s2, s2, s13
	s_add_u32 s8, s8, 0x70000
	s_addc_u32 s9, s9, 0
	v_mov_b32_e32 v0, s2
	v_mov_b32_e32 v1, 1
	s_waitcnt vmcnt(0) lgkmcnt(0)
	global_atomic_add v2, v0, v1, s[8:9] sc0
	s_mov_b32 s2, 0
	s_waitcnt vmcnt(0)
	v_readfirstlane_b32 s13, v2
	s_cmp_ge_u32 s13, 3
	s_cbranch_scc1 .Lmy_g3_own

.Lmy_gchk_5:
	s_mov_b32 s2, -1
	s_nop 0
	v_mbcnt_lo_u32_b32 v0, s2, 0
	v_mbcnt_hi_u32_b32 v0, s2, v0
	s_nop 0
	v_cmp_eq_u32_e32 vcc, 0, v0
	s_and_saveexec_b64 s[16:17], vcc
	s_cbranch_execz .LBB0_2218
	s_cmp_lg_u32 s101, 1
	s_cbranch_scc1 .Lmy_gfull_5
	v_readlane_b32 s2, v253, 37
	v_readlane_b32 s3, v250, 7
	v_readlane_b32 s8, v250, 0
	v_readlane_b32 s9, v250, 1
	s_lshl_b32 s2, s2, 12
	s_add_i32 s2, s2, 0x5000
	s_and_b32 s3, s3, 63
	s_lshl_b32 s3, s3, 6
	s_add_i32 s2, s2, s3
	s_add_u32 s8, s8, 0x70000
	s_addc_u32 s9, s9, 0
	v_mov_b32_e32 v0, s2
	v_mov_b32_e32 v1, 1
	s_waitcnt vmcnt(0) lgkmcnt(0)
	global_atomic_add v2, v0, v1, s[8:9] sc0
	s_mov_b32 s2, 0
	s_waitcnt vmcnt(0)
	v_readfirstlane_b32 s3, v2
	s_cmp_ge_u32 s3, 3
	s_cbranch_scc1 .Lmy_gdone_5

.Lmy_gchk_1:
	s_mov_b32 s2, -1
	s_nop 0
	v_mbcnt_lo_u32_b32 v0, s2, 0
	v_mbcnt_hi_u32_b32 v0, s2, v0
	s_nop 0
	v_cmp_eq_u32_e32 vcc, 0, v0
	s_and_saveexec_b64 s[16:17], vcc
	s_cbranch_execz .LBB0_2303
	s_cmp_lg_u32 s101, 1
	s_cbranch_scc1 .Lmy_gfull_1
	v_readlane_b32 s2, v253, 37
	v_readlane_b32 s3, v250, 7
	v_readlane_b32 s8, v250, 0
	v_readlane_b32 s9, v250, 1
	s_lshl_b32 s2, s2, 12
	s_add_i32 s2, s2, 0x1000
	s_and_b32 s3, s3, 63
	s_lshl_b32 s3, s3, 6
	s_add_i32 s2, s2, s3
	s_add_u32 s8, s8, 0x70000
	s_addc_u32 s9, s9, 0
	v_mov_b32_e32 v0, s2
	v_mov_b32_e32 v1, 1
	s_waitcnt vmcnt(0) lgkmcnt(0)
	global_atomic_add v2, v0, v1, s[8:9] sc0
	s_mov_b32 s2, 0
	s_waitcnt vmcnt(0)
	v_readfirstlane_b32 s3, v2
	s_cmp_ge_u32 s3, 3
	s_cbranch_scc1 .Lmy_gdone_1

.Lmy_gchk_2:
	s_mov_b32 s2, -1
	s_nop 0
	v_mbcnt_lo_u32_b32 v0, s2, 0
	v_mbcnt_hi_u32_b32 v0, s2, v0
	s_nop 0
	v_cmp_eq_u32_e32 vcc, 0, v0
	s_and_saveexec_b64 s[16:17], vcc
	s_cbranch_execz .LBB0_2381
	s_cmp_lg_u32 s101, 1
	s_cbranch_scc1 .Lmy_gfull_2
	v_readlane_b32 s2, v253, 37
	v_readlane_b32 s3, v250, 7
	v_readlane_b32 s8, v250, 0
	v_readlane_b32 s9, v250, 1
	s_lshl_b32 s2, s2, 12
	s_add_i32 s2, s2, 0x2000
	s_and_b32 s3, s3, 63
	s_lshl_b32 s3, s3, 6
	s_add_i32 s2, s2, s3
	s_add_u32 s8, s8, 0x70000
	s_addc_u32 s9, s9, 0
	v_mov_b32_e32 v0, s2
	v_mov_b32_e32 v1, 1
	s_waitcnt vmcnt(0) lgkmcnt(0)
	global_atomic_add v2, v0, v1, s[8:9] sc0
	s_mov_b32 s2, 0
	s_waitcnt vmcnt(0)
	v_readfirstlane_b32 s3, v2
	s_cmp_ge_u32 s3, 3
	s_cbranch_scc1 .Lmy_gdone_2
